# top-k threshold search: two tokens per iteration with interleaved bit-search chains (no early exit), original prologue/tail/write per token
# baseline (speedup 1.0000x reference)
.LBB0_157:
	s_add_i32 s2, s2, 1
	v_add_u32_e32 v0, 0x204, v0
	v_add_u32_e32 v21, 0, v0
	v_add_u32_e32 v2, 0x12100, v21
	v_add_u32_e32 v20, 0x14140, v21
	ds_read_b32 v3, v2
	ds_read_b32 v20, v20
	s_add_i32 s8, s0, s2
	s_ashr_i32 s12, s8, 6
	v_cmp_ge_i32_e32 vcc, s12, v210
	v_mov_b32_e32 v2, 0
	s_and_saveexec_b64 s[8:9], vcc
	s_cbranch_execz .Ltk1_pb
	v_add_u32_e32 v2, 0x12000, v21
	v_add_u32_e32 v21, 0x14040, v21
	ds_read_b32 v2, v2
	ds_read_b32 v21, v21
	v_cmp_eq_u32_e32 vcc, s12, v210
	s_or_b64 vcc, s[34:35], vcc
	s_waitcnt lgkmcnt(0)
	v_add_f32_e32 v2, v2, v21
	v_cndmask_b32_e32 v2, v2, v196, vcc
.Ltk1_pb:
	s_or_b64 exec, exec, s[8:9]
	s_waitcnt lgkmcnt(0)
	v_add_f32_e32 v3, v3, v20
	v_cmp_ne_u32_e32 vcc, s12, v219
	s_brev_b32 s9, -4
	s_nop 0
	v_cndmask_b32_e32 v3, v196, v3, vcc
	v_cmp_ge_i32_e32 vcc, s12, v219
	s_nop 1
	v_cndmask_b32_e32 v3, 0, v3, vcc
	v_cmp_lt_u32_e32 vcc, s9, v2
	s_bcnt1_i32_b64 s8, vcc
	v_cmp_lt_u32_e32 vcc, s9, v3
	s_bcnt1_i32_b64 s9, vcc
	s_add_i32 s9, s9, s8
	s_cmp_gt_u32 s9, 15
	s_cselect_b32 s8, 2.0, 0
	v_mov_b32_e32 v250, v2
	v_mov_b32_e32 v251, v3
	s_mov_b32 s44, s8
	s_add_i32 s2, s2, -1
	v_add_u32_e32 v0, 0xfffffdfc, v0
	v_add_u32_e32 v21, 0, v0
	v_add_u32_e32 v2, 0x12100, v21
	v_add_u32_e32 v20, 0x14140, v21
	ds_read_b32 v3, v2
	ds_read_b32 v20, v20
	s_add_i32 s8, s0, s2
	s_ashr_i32 s12, s8, 6
	v_cmp_ge_i32_e32 vcc, s12, v210
	v_mov_b32_e32 v2, 0
	s_and_saveexec_b64 s[8:9], vcc
	s_cbranch_execz .Ltk1_pa
	v_add_u32_e32 v2, 0x12000, v21
	v_add_u32_e32 v21, 0x14040, v21
	ds_read_b32 v2, v2
	ds_read_b32 v21, v21
	v_cmp_eq_u32_e32 vcc, s12, v210
	s_or_b64 vcc, s[34:35], vcc
	s_waitcnt lgkmcnt(0)
	v_add_f32_e32 v2, v2, v21
	v_cndmask_b32_e32 v2, v2, v196, vcc
.Ltk1_pa:
	s_or_b64 exec, exec, s[8:9]
	s_waitcnt lgkmcnt(0)
	v_add_f32_e32 v3, v3, v20
	v_cmp_ne_u32_e32 vcc, s12, v219
	s_brev_b32 s9, -4
	s_nop 0
	v_cndmask_b32_e32 v3, v196, v3, vcc
	v_cmp_ge_i32_e32 vcc, s12, v219
	s_nop 1
	v_cndmask_b32_e32 v3, 0, v3, vcc
	v_cmp_lt_u32_e32 vcc, s9, v2
	s_bcnt1_i32_b64 s8, vcc
	v_cmp_lt_u32_e32 vcc, s9, v3
	s_bcnt1_i32_b64 s9, vcc
	s_add_i32 s9, s9, s8
	s_cmp_gt_u32 s9, 15
	s_cselect_b32 s8, 2.0, 0
	s_or_b32 s9, s8, 0x20000000
	s_or_b32 s45, s44, 0x20000000
	v_cmp_le_u32_e32 vcc, s9, v2
	v_cmp_le_u32_e64 s[48:49], s45, v250
	s_bcnt1_i32_b64 s12, vcc
	s_bcnt1_i32_b64 s46, s[48:49]
	s_cmp_gt_u32 s12, 15
	s_cselect_b32 s8, s9, s8
	s_cmp_gt_u32 s46, 15
	s_cselect_b32 s44, s45, s44
	s_or_b32 s9, s8, 0x10000000
	s_or_b32 s45, s44, 0x10000000
	v_cmp_le_u32_e32 vcc, s9, v2
	v_cmp_le_u32_e64 s[48:49], s45, v250
	s_bcnt1_i32_b64 s12, vcc
	s_bcnt1_i32_b64 s46, s[48:49]
	s_cmp_gt_u32 s12, 15
	s_cselect_b32 s8, s9, s8
	s_cmp_gt_u32 s46, 15
	s_cselect_b32 s44, s45, s44
	s_or_b32 s9, s8, 0x8000000
	s_or_b32 s45, s44, 0x8000000
	v_cmp_le_u32_e32 vcc, s9, v2
	v_cmp_le_u32_e64 s[48:49], s45, v250
	s_bcnt1_i32_b64 s12, vcc
	s_bcnt1_i32_b64 s46, s[48:49]
	s_cmp_gt_u32 s12, 15
	s_cselect_b32 s8, s9, s8
	s_cmp_gt_u32 s46, 15
	s_cselect_b32 s44, s45, s44
	s_or_b32 s9, s8, 0x4000000
	s_or_b32 s45, s44, 0x4000000
	v_cmp_le_u32_e32 vcc, s9, v2
	v_cmp_le_u32_e64 s[48:49], s45, v250
	s_bcnt1_i32_b64 s12, vcc
	s_bcnt1_i32_b64 s46, s[48:49]
	s_cmp_gt_u32 s12, 15
	s_cselect_b32 s8, s9, s8
	s_cmp_gt_u32 s46, 15
	s_cselect_b32 s44, s45, s44
	s_or_b32 s9, s8, 0x2000000
	s_or_b32 s45, s44, 0x2000000
	v_cmp_le_u32_e32 vcc, s9, v2
	v_cmp_le_u32_e64 s[48:49], s45, v250
	s_bcnt1_i32_b64 s12, vcc
	s_bcnt1_i32_b64 s46, s[48:49]
	s_cmp_gt_u32 s12, 15
	s_cselect_b32 s8, s9, s8
	s_cmp_gt_u32 s46, 15
	s_cselect_b32 s44, s45, s44
	s_or_b32 s9, s8, 0x1000000
	s_or_b32 s45, s44, 0x1000000
	v_cmp_le_u32_e32 vcc, s9, v2
	v_cmp_le_u32_e64 s[48:49], s45, v250
	s_bcnt1_i32_b64 s12, vcc
	s_bcnt1_i32_b64 s46, s[48:49]
	s_cmp_gt_u32 s12, 15
	s_cselect_b32 s8, s9, s8
	s_cmp_gt_u32 s46, 15
	s_cselect_b32 s44, s45, s44
	s_or_b32 s9, s8, 0x800000
	s_or_b32 s45, s44, 0x800000
	v_cmp_le_u32_e32 vcc, s9, v2
	v_cmp_le_u32_e64 s[48:49], s45, v250
	s_bcnt1_i32_b64 s12, vcc
	s_bcnt1_i32_b64 s46, s[48:49]
	s_cmp_gt_u32 s12, 15
	s_cselect_b32 s8, s9, s8
	s_cmp_gt_u32 s46, 15
	s_cselect_b32 s44, s45, s44
	s_or_b32 s9, s8, 0x400000
	s_or_b32 s45, s44, 0x400000
	v_cmp_le_u32_e32 vcc, s9, v2
	v_cmp_le_u32_e64 s[48:49], s45, v250
	s_bcnt1_i32_b64 s12, vcc
	s_bcnt1_i32_b64 s46, s[48:49]
	s_cmp_gt_u32 s12, 15
	s_cselect_b32 s8, s9, s8
	s_cmp_gt_u32 s46, 15
	s_cselect_b32 s44, s45, s44
	s_or_b32 s9, s8, 0x200000
	s_or_b32 s45, s44, 0x200000
	v_cmp_le_u32_e32 vcc, s9, v2
	v_cmp_le_u32_e64 s[48:49], s45, v250
	s_bcnt1_i32_b64 s12, vcc
	s_bcnt1_i32_b64 s46, s[48:49]
	s_cmp_gt_u32 s12, 15
	s_cselect_b32 s8, s9, s8
	s_cmp_gt_u32 s46, 15
	s_cselect_b32 s44, s45, s44
	s_or_b32 s9, s8, 0x100000
	s_or_b32 s45, s44, 0x100000
	v_cmp_le_u32_e32 vcc, s9, v2
	v_cmp_le_u32_e64 s[48:49], s45, v250
	s_bcnt1_i32_b64 s12, vcc
	s_bcnt1_i32_b64 s46, s[48:49]
	s_cmp_gt_u32 s12, 15
	s_cselect_b32 s8, s9, s8
	s_cmp_gt_u32 s46, 15
	s_cselect_b32 s44, s45, s44
	s_or_b32 s9, s8, 0x80000
	s_or_b32 s45, s44, 0x80000
	v_cmp_le_u32_e32 vcc, s9, v2
	v_cmp_le_u32_e64 s[48:49], s45, v250
	s_bcnt1_i32_b64 s12, vcc
	s_bcnt1_i32_b64 s46, s[48:49]
	s_cmp_gt_u32 s12, 15
	s_cselect_b32 s8, s9, s8
	s_cmp_gt_u32 s46, 15
	s_cselect_b32 s44, s45, s44
	s_or_b32 s9, s8, 0x40000
	s_or_b32 s45, s44, 0x40000
	v_cmp_le_u32_e32 vcc, s9, v2
	v_cmp_le_u32_e64 s[48:49], s45, v250
	s_bcnt1_i32_b64 s12, vcc
	s_bcnt1_i32_b64 s46, s[48:49]
	s_cmp_gt_u32 s12, 15
	s_cselect_b32 s8, s9, s8
	s_cmp_gt_u32 s46, 15
	s_cselect_b32 s44, s45, s44
	s_or_b32 s9, s8, 0x20000
	s_or_b32 s45, s44, 0x20000
	v_cmp_le_u32_e32 vcc, s9, v2
	v_cmp_le_u32_e64 s[48:49], s45, v250
	s_bcnt1_i32_b64 s12, vcc
	s_bcnt1_i32_b64 s46, s[48:49]
	s_cmp_gt_u32 s12, 15
	s_cselect_b32 s8, s9, s8
	s_cmp_gt_u32 s46, 15
	s_cselect_b32 s44, s45, s44
	s_or_b32 s9, s8, 0x10000
	s_or_b32 s45, s44, 0x10000
	v_cmp_le_u32_e32 vcc, s9, v2
	v_cmp_le_u32_e64 s[48:49], s45, v250
	s_bcnt1_i32_b64 s12, vcc
	s_bcnt1_i32_b64 s46, s[48:49]
	s_cmp_gt_u32 s12, 15
	s_cselect_b32 s8, s9, s8
	s_cmp_gt_u32 s46, 15
	s_cselect_b32 s44, s45, s44
	s_or_b32 s9, s8, 0x8000
	s_or_b32 s45, s44, 0x8000
	v_cmp_le_u32_e32 vcc, s9, v2
	v_cmp_le_u32_e64 s[48:49], s45, v250
	s_bcnt1_i32_b64 s12, vcc
	s_bcnt1_i32_b64 s46, s[48:49]
	s_cmp_gt_u32 s12, 15
	s_cselect_b32 s8, s9, s8
	s_cmp_gt_u32 s46, 15
	s_cselect_b32 s44, s45, s44
	s_or_b32 s9, s8, 0x4000
	s_or_b32 s45, s44, 0x4000
	v_cmp_le_u32_e32 vcc, s9, v2
	v_cmp_le_u32_e64 s[48:49], s45, v250
	s_bcnt1_i32_b64 s12, vcc
	s_bcnt1_i32_b64 s46, s[48:49]
	s_cmp_gt_u32 s12, 15
	s_cselect_b32 s8, s9, s8
	s_cmp_gt_u32 s46, 15
	s_cselect_b32 s44, s45, s44
	s_or_b32 s9, s8, 0x2000
	s_or_b32 s45, s44, 0x2000
	v_cmp_le_u32_e32 vcc, s9, v2
	v_cmp_le_u32_e64 s[48:49], s45, v250
	s_bcnt1_i32_b64 s12, vcc
	s_bcnt1_i32_b64 s46, s[48:49]
	s_cmp_gt_u32 s12, 15
	s_cselect_b32 s8, s9, s8
	s_cmp_gt_u32 s46, 15
	s_cselect_b32 s44, s45, s44
	s_or_b32 s9, s8, 0x1000
	s_or_b32 s45, s44, 0x1000
	v_cmp_le_u32_e32 vcc, s9, v2
	v_cmp_le_u32_e64 s[48:49], s45, v250
	s_bcnt1_i32_b64 s12, vcc
	s_bcnt1_i32_b64 s46, s[48:49]
	s_cmp_gt_u32 s12, 15
	s_cselect_b32 s8, s9, s8
	s_cmp_gt_u32 s46, 15
	s_cselect_b32 s44, s45, s44
	s_or_b32 s9, s8, 0x800
	s_or_b32 s45, s44, 0x800
	v_cmp_le_u32_e32 vcc, s9, v2
	v_cmp_le_u32_e64 s[48:49], s45, v250
	s_bcnt1_i32_b64 s12, vcc
	s_bcnt1_i32_b64 s46, s[48:49]
	s_cmp_gt_u32 s12, 15
	s_cselect_b32 s8, s9, s8
	s_cmp_gt_u32 s46, 15
	s_cselect_b32 s44, s45, s44
	s_or_b32 s9, s8, 0x400
	s_or_b32 s45, s44, 0x400
	v_cmp_le_u32_e32 vcc, s9, v2
	v_cmp_le_u32_e64 s[48:49], s45, v250
	s_bcnt1_i32_b64 s12, vcc
	s_bcnt1_i32_b64 s46, s[48:49]
	s_cmp_gt_u32 s12, 15
	s_cselect_b32 s8, s9, s8
	s_cmp_gt_u32 s46, 15
	s_cselect_b32 s44, s45, s44
	s_or_b32 s9, s8, 0x200
	s_or_b32 s45, s44, 0x200
	v_cmp_le_u32_e32 vcc, s9, v2
	v_cmp_le_u32_e64 s[48:49], s45, v250
	s_bcnt1_i32_b64 s12, vcc
	s_bcnt1_i32_b64 s46, s[48:49]
	s_cmp_gt_u32 s12, 15
	s_cselect_b32 s8, s9, s8
	s_cmp_gt_u32 s46, 15
	s_cselect_b32 s44, s45, s44
	s_or_b32 s9, s8, 0x100
	s_or_b32 s45, s44, 0x100
	v_cmp_le_u32_e32 vcc, s9, v2
	v_cmp_le_u32_e64 s[48:49], s45, v250
	s_bcnt1_i32_b64 s12, vcc
	s_bcnt1_i32_b64 s46, s[48:49]
	s_cmp_gt_u32 s12, 15
	s_cselect_b32 s8, s9, s8
	s_cmp_gt_u32 s46, 15
	s_cselect_b32 s44, s45, s44
	s_or_b32 s9, s8, 0x80
	s_or_b32 s45, s44, 0x80
	v_cmp_le_u32_e32 vcc, s9, v2
	v_cmp_le_u32_e64 s[48:49], s45, v250
	s_bcnt1_i32_b64 s12, vcc
	s_bcnt1_i32_b64 s46, s[48:49]
	s_cmp_gt_u32 s12, 15
	s_cselect_b32 s8, s9, s8
	s_cmp_gt_u32 s46, 15
	s_cselect_b32 s44, s45, s44
	s_or_b32 s9, s8, 64
	s_or_b32 s45, s44, 64
	v_cmp_le_u32_e32 vcc, s9, v2
	v_cmp_le_u32_e64 s[48:49], s45, v250
	s_bcnt1_i32_b64 s12, vcc
	s_bcnt1_i32_b64 s46, s[48:49]
	s_cmp_gt_u32 s12, 15
	s_cselect_b32 s8, s9, s8
	s_cmp_gt_u32 s46, 15
	s_cselect_b32 s44, s45, s44
	s_or_b32 s9, s8, 32
	s_or_b32 s45, s44, 32
	v_cmp_le_u32_e32 vcc, s9, v2
	v_cmp_le_u32_e64 s[48:49], s45, v250
	s_bcnt1_i32_b64 s12, vcc
	s_bcnt1_i32_b64 s46, s[48:49]
	s_cmp_gt_u32 s12, 15
	s_cselect_b32 s8, s9, s8
	s_cmp_gt_u32 s46, 15
	s_cselect_b32 s44, s45, s44
	s_or_b32 s9, s8, 16
	s_or_b32 s45, s44, 16
	v_cmp_le_u32_e32 vcc, s9, v2
	v_cmp_le_u32_e64 s[48:49], s45, v250
	s_bcnt1_i32_b64 s12, vcc
	s_bcnt1_i32_b64 s46, s[48:49]
	s_cmp_gt_u32 s12, 15
	s_cselect_b32 s8, s9, s8
	s_cmp_gt_u32 s46, 15
	s_cselect_b32 s44, s45, s44
	s_or_b32 s9, s8, 8
	s_or_b32 s45, s44, 8
	v_cmp_le_u32_e32 vcc, s9, v2
	v_cmp_le_u32_e64 s[48:49], s45, v250
	s_bcnt1_i32_b64 s12, vcc
	s_bcnt1_i32_b64 s46, s[48:49]
	s_cmp_gt_u32 s12, 15
	s_cselect_b32 s8, s9, s8
	s_cmp_gt_u32 s46, 15
	s_cselect_b32 s44, s45, s44
	s_or_b32 s9, s8, 4
	s_or_b32 s45, s44, 4
	v_cmp_le_u32_e32 vcc, s9, v2
	v_cmp_le_u32_e64 s[48:49], s45, v250
	s_bcnt1_i32_b64 s12, vcc
	s_bcnt1_i32_b64 s46, s[48:49]
	s_cmp_gt_u32 s12, 15
	s_cselect_b32 s8, s9, s8
	s_cmp_gt_u32 s46, 15
	s_cselect_b32 s44, s45, s44
	s_or_b32 s9, s8, 2
	s_or_b32 s45, s44, 2
	v_cmp_le_u32_e32 vcc, s9, v2
	v_cmp_le_u32_e64 s[48:49], s45, v250
	s_bcnt1_i32_b64 s12, vcc
	s_bcnt1_i32_b64 s46, s[48:49]
	s_cmp_gt_u32 s12, 15
	s_cselect_b32 s8, s9, s8
	s_cmp_gt_u32 s46, 15
	s_cselect_b32 s44, s45, s44
	s_or_b32 s9, s8, 1
	s_or_b32 s45, s44, 1
	v_cmp_le_u32_e32 vcc, s9, v2
	v_cmp_le_u32_e64 s[48:49], s45, v250
	s_bcnt1_i32_b64 s12, vcc
	s_bcnt1_i32_b64 s46, s[48:49]
	s_cmp_gt_u32 s12, 15
	s_cselect_b32 s8, s9, s8
	s_cmp_gt_u32 s46, 15
	s_cselect_b32 s44, s45, s44
	v_cmp_eq_u32_e64 s[38:39], s8, v2
	v_cmp_lt_u32_e32 vcc, s8, v2
	v_cmp_lt_u32_e64 s[36:37], s8, v3
	v_cmp_eq_u32_e64 s[40:41], s8, v3
	v_and_b32_e32 v3, s38, v170
	s_bcnt1_i32_b64 s9, vcc
	s_bcnt1_i32_b64 s12, s[36:37]
	v_and_b32_e32 v2, s39, v163
	v_bcnt_u32_b32 v3, v3, 0
	v_and_b32_e32 v20, s40, v170
	s_add_i32 s9, s9, s12
	v_bcnt_u32_b32 v2, v2, v3
	v_and_b32_e32 v3, s41, v163
	v_bcnt_u32_b32 v20, v20, 0
	s_sub_i32 s12, 16, s9
	s_bcnt1_i32_b64 s8, s[38:39]
	v_bcnt_u32_b32 v3, v3, v20
	v_add_u32_e32 v3, s8, v3
	v_cmp_gt_i32_e64 s[42:43], s12, v2
	s_and_b64 s[8:9], s[38:39], s[42:43]
	v_cmp_gt_i32_e64 s[38:39], s12, v3
	s_and_b64 s[14:15], s[40:41], s[38:39]
	s_or_b64 s[8:9], vcc, s[8:9]
	v_cndmask_b32_e64 v2, 0, 1, s[8:9]
	s_or_b64 s[8:9], s[36:37], s[14:15]
	v_cmp_ne_u32_e64 s[12:13], 0, v2
	v_cndmask_b32_e64 v2, 0, 1, s[8:9]
	v_cmp_ne_u32_e32 vcc, 0, v2
	s_and_saveexec_b64 s[8:9], s[34:35]
	s_cbranch_execz .Ltk1_wa
	s_add_i32 s14, s3, 0
	s_add_i32 s14, s14, 0x22200
	v_mov_b32_e32 v20, s12
	v_mov_b32_e32 v21, s13
	v_mov_b32_e32 v22, vcc_lo
	v_mov_b32_e32 v23, vcc_hi
	v_mov_b32_e32 v2, s14
	ds_write_b128 v2, v[20:23]
.Ltk1_wa:
	s_or_b64 exec, exec, s[8:9]
	s_nop 3
	s_mov_b32 s8, s44
	v_mov_b32_e32 v2, v250
	v_mov_b32_e32 v3, v251
	s_add_i32 s3, s3, 16
	v_cmp_eq_u32_e64 s[38:39], s8, v2
	v_cmp_lt_u32_e32 vcc, s8, v2
	v_cmp_lt_u32_e64 s[36:37], s8, v3
	v_cmp_eq_u32_e64 s[40:41], s8, v3
	v_and_b32_e32 v3, s38, v170
	s_bcnt1_i32_b64 s9, vcc
	s_bcnt1_i32_b64 s12, s[36:37]
	v_and_b32_e32 v2, s39, v163
	v_bcnt_u32_b32 v3, v3, 0
	v_and_b32_e32 v20, s40, v170
	s_add_i32 s9, s9, s12
	v_bcnt_u32_b32 v2, v2, v3
	v_and_b32_e32 v3, s41, v163
	v_bcnt_u32_b32 v20, v20, 0
	s_sub_i32 s12, 16, s9
	s_bcnt1_i32_b64 s8, s[38:39]
	v_bcnt_u32_b32 v3, v3, v20
	v_add_u32_e32 v3, s8, v3
	v_cmp_gt_i32_e64 s[42:43], s12, v2
	s_and_b64 s[8:9], s[38:39], s[42:43]
	v_cmp_gt_i32_e64 s[38:39], s12, v3
	s_and_b64 s[14:15], s[40:41], s[38:39]
	s_or_b64 s[8:9], vcc, s[8:9]
	v_cndmask_b32_e64 v2, 0, 1, s[8:9]
	s_or_b64 s[8:9], s[36:37], s[14:15]
	v_cmp_ne_u32_e64 s[12:13], 0, v2
	v_cndmask_b32_e64 v2, 0, 1, s[8:9]
	v_cmp_ne_u32_e32 vcc, 0, v2
	s_and_saveexec_b64 s[8:9], s[34:35]
	s_cbranch_execz .Ltk1_wb
	s_add_i32 s14, s3, 0
	s_add_i32 s14, s14, 0x22200
	v_mov_b32_e32 v20, s12
	v_mov_b32_e32 v21, s13
	v_mov_b32_e32 v22, vcc_lo
	v_mov_b32_e32 v23, vcc_hi
	v_mov_b32_e32 v2, s14
	ds_write_b128 v2, v[20:23]
.Ltk1_wb:
	s_or_b64 exec, exec, s[8:9]
	s_add_i32 s3, s3, 16
	s_add_i32 s2, s2, 2
	v_add_u32_e32 v0, 0x408, v0
	s_cmp_eq_u32 s2, 8
	s_cbranch_scc0 .LBB0_157

.LBB0_234:
	s_add_i32 s6, s6, 1
	v_add_u32_e32 v0, 0x204, v0
	v_add_u32_e32 v21, 0, v0
	v_add_u32_e32 v2, 0x12100, v21
	v_add_u32_e32 v20, 0x14140, v21
	ds_read_b32 v3, v2
	ds_read_b32 v20, v20
	s_add_i32 s2, s0, s6
	s_ashr_i32 s12, s2, 6
	v_cmp_ge_i32_e32 vcc, s12, v210
	v_mov_b32_e32 v2, 0
	s_and_saveexec_b64 s[2:3], vcc
	s_cbranch_execz .Ltk2_pb
	v_add_u32_e32 v2, 0x12000, v21
	v_add_u32_e32 v21, 0x14040, v21
	ds_read_b32 v2, v2
	ds_read_b32 v21, v21
	v_cmp_eq_u32_e32 vcc, s12, v210
	s_or_b64 vcc, s[34:35], vcc
	s_waitcnt lgkmcnt(0)
	v_add_f32_e32 v2, v2, v21
	v_cndmask_b32_e32 v2, v2, v196, vcc
.Ltk2_pb:
	s_or_b64 exec, exec, s[2:3]
	s_waitcnt lgkmcnt(0)
	v_add_f32_e32 v3, v3, v20
	v_cmp_ne_u32_e32 vcc, s12, v219
	s_brev_b32 s3, -4
	s_nop 0
	v_cndmask_b32_e32 v3, v196, v3, vcc
	v_cmp_ge_i32_e32 vcc, s12, v219
	s_nop 1
	v_cndmask_b32_e32 v3, 0, v3, vcc
	v_cmp_lt_u32_e32 vcc, s3, v2
	s_bcnt1_i32_b64 s2, vcc
	v_cmp_lt_u32_e32 vcc, s3, v3
	s_bcnt1_i32_b64 s3, vcc
	s_add_i32 s3, s3, s2
	s_cmp_gt_u32 s3, 15
	s_cselect_b32 s2, 2.0, 0
	v_mov_b32_e32 v250, v2
	v_mov_b32_e32 v251, v3
	s_mov_b32 s44, s2
	s_add_i32 s6, s6, -1
	v_add_u32_e32 v0, 0xfffffdfc, v0
	v_add_u32_e32 v21, 0, v0
	v_add_u32_e32 v2, 0x12100, v21
	v_add_u32_e32 v20, 0x14140, v21
	ds_read_b32 v3, v2
	ds_read_b32 v20, v20
	s_add_i32 s2, s0, s6
	s_ashr_i32 s12, s2, 6
	v_cmp_ge_i32_e32 vcc, s12, v210
	v_mov_b32_e32 v2, 0
	s_and_saveexec_b64 s[2:3], vcc
	s_cbranch_execz .Ltk2_pa
	v_add_u32_e32 v2, 0x12000, v21
	v_add_u32_e32 v21, 0x14040, v21
	ds_read_b32 v2, v2
	ds_read_b32 v21, v21
	v_cmp_eq_u32_e32 vcc, s12, v210
	s_or_b64 vcc, s[34:35], vcc
	s_waitcnt lgkmcnt(0)
	v_add_f32_e32 v2, v2, v21
	v_cndmask_b32_e32 v2, v2, v196, vcc
.Ltk2_pa:
	s_or_b64 exec, exec, s[2:3]
	s_waitcnt lgkmcnt(0)
	v_add_f32_e32 v3, v3, v20
	v_cmp_ne_u32_e32 vcc, s12, v219
	s_brev_b32 s3, -4
	s_nop 0
	v_cndmask_b32_e32 v3, v196, v3, vcc
	v_cmp_ge_i32_e32 vcc, s12, v219
	s_nop 1
	v_cndmask_b32_e32 v3, 0, v3, vcc
	v_cmp_lt_u32_e32 vcc, s3, v2
	s_bcnt1_i32_b64 s2, vcc
	v_cmp_lt_u32_e32 vcc, s3, v3
	s_bcnt1_i32_b64 s3, vcc
	s_add_i32 s3, s3, s2
	s_cmp_gt_u32 s3, 15
	s_cselect_b32 s2, 2.0, 0
	s_or_b32 s3, s2, 0x20000000
	s_or_b32 s45, s44, 0x20000000
	v_cmp_le_u32_e64 s[36:37], s3, v2
	v_cmp_le_u32_e32 vcc, s3, v3
	v_cmp_le_u32_e64 s[48:49], s45, v250
	v_cmp_le_u32_e64 s[50:51], s45, v251
	s_bcnt1_i32_b64 s12, s[36:37]
	s_bcnt1_i32_b64 s13, vcc
	s_bcnt1_i32_b64 s46, s[48:49]
	s_bcnt1_i32_b64 s47, s[50:51]
	s_add_i32 s13, s13, s12
	s_add_i32 s47, s47, s46
	s_cmp_gt_u32 s13, 15
	s_cselect_b32 s2, s3, s2
	s_cmp_gt_u32 s47, 15
	s_cselect_b32 s44, s45, s44
	s_or_b32 s3, s2, 0x10000000
	s_or_b32 s45, s44, 0x10000000
	v_cmp_le_u32_e64 s[36:37], s3, v2
	v_cmp_le_u32_e32 vcc, s3, v3
	v_cmp_le_u32_e64 s[48:49], s45, v250
	v_cmp_le_u32_e64 s[50:51], s45, v251
	s_bcnt1_i32_b64 s12, s[36:37]
	s_bcnt1_i32_b64 s13, vcc
	s_bcnt1_i32_b64 s46, s[48:49]
	s_bcnt1_i32_b64 s47, s[50:51]
	s_add_i32 s13, s13, s12
	s_add_i32 s47, s47, s46
	s_cmp_gt_u32 s13, 15
	s_cselect_b32 s2, s3, s2
	s_cmp_gt_u32 s47, 15
	s_cselect_b32 s44, s45, s44
	s_or_b32 s3, s2, 0x8000000
	s_or_b32 s45, s44, 0x8000000
	v_cmp_le_u32_e64 s[36:37], s3, v2
	v_cmp_le_u32_e32 vcc, s3, v3
	v_cmp_le_u32_e64 s[48:49], s45, v250
	v_cmp_le_u32_e64 s[50:51], s45, v251
	s_bcnt1_i32_b64 s12, s[36:37]
	s_bcnt1_i32_b64 s13, vcc
	s_bcnt1_i32_b64 s46, s[48:49]
	s_bcnt1_i32_b64 s47, s[50:51]
	s_add_i32 s13, s13, s12
	s_add_i32 s47, s47, s46
	s_cmp_gt_u32 s13, 15
	s_cselect_b32 s2, s3, s2
	s_cmp_gt_u32 s47, 15
	s_cselect_b32 s44, s45, s44
	s_or_b32 s3, s2, 0x4000000
	s_or_b32 s45, s44, 0x4000000
	v_cmp_le_u32_e64 s[36:37], s3, v2
	v_cmp_le_u32_e32 vcc, s3, v3
	v_cmp_le_u32_e64 s[48:49], s45, v250
	v_cmp_le_u32_e64 s[50:51], s45, v251
	s_bcnt1_i32_b64 s12, s[36:37]
	s_bcnt1_i32_b64 s13, vcc
	s_bcnt1_i32_b64 s46, s[48:49]
	s_bcnt1_i32_b64 s47, s[50:51]
	s_add_i32 s13, s13, s12
	s_add_i32 s47, s47, s46
	s_cmp_gt_u32 s13, 15
	s_cselect_b32 s2, s3, s2
	s_cmp_gt_u32 s47, 15
	s_cselect_b32 s44, s45, s44
	s_or_b32 s3, s2, 0x2000000
	s_or_b32 s45, s44, 0x2000000
	v_cmp_le_u32_e64 s[36:37], s3, v2
	v_cmp_le_u32_e32 vcc, s3, v3
	v_cmp_le_u32_e64 s[48:49], s45, v250
	v_cmp_le_u32_e64 s[50:51], s45, v251
	s_bcnt1_i32_b64 s12, s[36:37]
	s_bcnt1_i32_b64 s13, vcc
	s_bcnt1_i32_b64 s46, s[48:49]
	s_bcnt1_i32_b64 s47, s[50:51]
	s_add_i32 s13, s13, s12
	s_add_i32 s47, s47, s46
	s_cmp_gt_u32 s13, 15
	s_cselect_b32 s2, s3, s2
	s_cmp_gt_u32 s47, 15
	s_cselect_b32 s44, s45, s44
	s_or_b32 s3, s2, 0x1000000
	s_or_b32 s45, s44, 0x1000000
	v_cmp_le_u32_e64 s[36:37], s3, v2
	v_cmp_le_u32_e32 vcc, s3, v3
	v_cmp_le_u32_e64 s[48:49], s45, v250
	v_cmp_le_u32_e64 s[50:51], s45, v251
	s_bcnt1_i32_b64 s12, s[36:37]
	s_bcnt1_i32_b64 s13, vcc
	s_bcnt1_i32_b64 s46, s[48:49]
	s_bcnt1_i32_b64 s47, s[50:51]
	s_add_i32 s13, s13, s12
	s_add_i32 s47, s47, s46
	s_cmp_gt_u32 s13, 15
	s_cselect_b32 s2, s3, s2
	s_cmp_gt_u32 s47, 15
	s_cselect_b32 s44, s45, s44
	s_or_b32 s3, s2, 0x800000
	s_or_b32 s45, s44, 0x800000
	v_cmp_le_u32_e64 s[36:37], s3, v2
	v_cmp_le_u32_e32 vcc, s3, v3
	v_cmp_le_u32_e64 s[48:49], s45, v250
	v_cmp_le_u32_e64 s[50:51], s45, v251
	s_bcnt1_i32_b64 s12, s[36:37]
	s_bcnt1_i32_b64 s13, vcc
	s_bcnt1_i32_b64 s46, s[48:49]
	s_bcnt1_i32_b64 s47, s[50:51]
	s_add_i32 s13, s13, s12
	s_add_i32 s47, s47, s46
	s_cmp_gt_u32 s13, 15
	s_cselect_b32 s2, s3, s2
	s_cmp_gt_u32 s47, 15
	s_cselect_b32 s44, s45, s44
	s_or_b32 s3, s2, 0x400000
	s_or_b32 s45, s44, 0x400000
	v_cmp_le_u32_e64 s[36:37], s3, v2
	v_cmp_le_u32_e32 vcc, s3, v3
	v_cmp_le_u32_e64 s[48:49], s45, v250
	v_cmp_le_u32_e64 s[50:51], s45, v251
	s_bcnt1_i32_b64 s12, s[36:37]
	s_bcnt1_i32_b64 s13, vcc
	s_bcnt1_i32_b64 s46, s[48:49]
	s_bcnt1_i32_b64 s47, s[50:51]
	s_add_i32 s13, s13, s12
	s_add_i32 s47, s47, s46
	s_cmp_gt_u32 s13, 15
	s_cselect_b32 s2, s3, s2
	s_cmp_gt_u32 s47, 15
	s_cselect_b32 s44, s45, s44
	s_or_b32 s3, s2, 0x200000
	s_or_b32 s45, s44, 0x200000
	v_cmp_le_u32_e64 s[36:37], s3, v2
	v_cmp_le_u32_e32 vcc, s3, v3
	v_cmp_le_u32_e64 s[48:49], s45, v250
	v_cmp_le_u32_e64 s[50:51], s45, v251
	s_bcnt1_i32_b64 s12, s[36:37]
	s_bcnt1_i32_b64 s13, vcc
	s_bcnt1_i32_b64 s46, s[48:49]
	s_bcnt1_i32_b64 s47, s[50:51]
	s_add_i32 s13, s13, s12
	s_add_i32 s47, s47, s46
	s_cmp_gt_u32 s13, 15
	s_cselect_b32 s2, s3, s2
	s_cmp_gt_u32 s47, 15
	s_cselect_b32 s44, s45, s44
	s_or_b32 s3, s2, 0x100000
	s_or_b32 s45, s44, 0x100000
	v_cmp_le_u32_e64 s[36:37], s3, v2
	v_cmp_le_u32_e32 vcc, s3, v3
	v_cmp_le_u32_e64 s[48:49], s45, v250
	v_cmp_le_u32_e64 s[50:51], s45, v251
	s_bcnt1_i32_b64 s12, s[36:37]
	s_bcnt1_i32_b64 s13, vcc
	s_bcnt1_i32_b64 s46, s[48:49]
	s_bcnt1_i32_b64 s47, s[50:51]
	s_add_i32 s13, s13, s12
	s_add_i32 s47, s47, s46
	s_cmp_gt_u32 s13, 15
	s_cselect_b32 s2, s3, s2
	s_cmp_gt_u32 s47, 15
	s_cselect_b32 s44, s45, s44
	s_or_b32 s3, s2, 0x80000
	s_or_b32 s45, s44, 0x80000
	v_cmp_le_u32_e64 s[36:37], s3, v2
	v_cmp_le_u32_e32 vcc, s3, v3
	v_cmp_le_u32_e64 s[48:49], s45, v250
	v_cmp_le_u32_e64 s[50:51], s45, v251
	s_bcnt1_i32_b64 s12, s[36:37]
	s_bcnt1_i32_b64 s13, vcc
	s_bcnt1_i32_b64 s46, s[48:49]
	s_bcnt1_i32_b64 s47, s[50:51]
	s_add_i32 s13, s13, s12
	s_add_i32 s47, s47, s46
	s_cmp_gt_u32 s13, 15
	s_cselect_b32 s2, s3, s2
	s_cmp_gt_u32 s47, 15
	s_cselect_b32 s44, s45, s44
	s_or_b32 s3, s2, 0x40000
	s_or_b32 s45, s44, 0x40000
	v_cmp_le_u32_e64 s[36:37], s3, v2
	v_cmp_le_u32_e32 vcc, s3, v3
	v_cmp_le_u32_e64 s[48:49], s45, v250
	v_cmp_le_u32_e64 s[50:51], s45, v251
	s_bcnt1_i32_b64 s12, s[36:37]
	s_bcnt1_i32_b64 s13, vcc
	s_bcnt1_i32_b64 s46, s[48:49]
	s_bcnt1_i32_b64 s47, s[50:51]
	s_add_i32 s13, s13, s12
	s_add_i32 s47, s47, s46
	s_cmp_gt_u32 s13, 15
	s_cselect_b32 s2, s3, s2
	s_cmp_gt_u32 s47, 15
	s_cselect_b32 s44, s45, s44
	s_or_b32 s3, s2, 0x20000
	s_or_b32 s45, s44, 0x20000
	v_cmp_le_u32_e64 s[36:37], s3, v2
	v_cmp_le_u32_e32 vcc, s3, v3
	v_cmp_le_u32_e64 s[48:49], s45, v250
	v_cmp_le_u32_e64 s[50:51], s45, v251
	s_bcnt1_i32_b64 s12, s[36:37]
	s_bcnt1_i32_b64 s13, vcc
	s_bcnt1_i32_b64 s46, s[48:49]
	s_bcnt1_i32_b64 s47, s[50:51]
	s_add_i32 s13, s13, s12
	s_add_i32 s47, s47, s46
	s_cmp_gt_u32 s13, 15
	s_cselect_b32 s2, s3, s2
	s_cmp_gt_u32 s47, 15
	s_cselect_b32 s44, s45, s44
	s_or_b32 s3, s2, 0x10000
	s_or_b32 s45, s44, 0x10000
	v_cmp_le_u32_e64 s[36:37], s3, v2
	v_cmp_le_u32_e32 vcc, s3, v3
	v_cmp_le_u32_e64 s[48:49], s45, v250
	v_cmp_le_u32_e64 s[50:51], s45, v251
	s_bcnt1_i32_b64 s12, s[36:37]
	s_bcnt1_i32_b64 s13, vcc
	s_bcnt1_i32_b64 s46, s[48:49]
	s_bcnt1_i32_b64 s47, s[50:51]
	s_add_i32 s13, s13, s12
	s_add_i32 s47, s47, s46
	s_cmp_gt_u32 s13, 15
	s_cselect_b32 s2, s3, s2
	s_cmp_gt_u32 s47, 15
	s_cselect_b32 s44, s45, s44
	s_or_b32 s3, s2, 0x8000
	s_or_b32 s45, s44, 0x8000
	v_cmp_le_u32_e64 s[36:37], s3, v2
	v_cmp_le_u32_e32 vcc, s3, v3
	v_cmp_le_u32_e64 s[48:49], s45, v250
	v_cmp_le_u32_e64 s[50:51], s45, v251
	s_bcnt1_i32_b64 s12, s[36:37]
	s_bcnt1_i32_b64 s13, vcc
	s_bcnt1_i32_b64 s46, s[48:49]
	s_bcnt1_i32_b64 s47, s[50:51]
	s_add_i32 s13, s13, s12
	s_add_i32 s47, s47, s46
	s_cmp_gt_u32 s13, 15
	s_cselect_b32 s2, s3, s2
	s_cmp_gt_u32 s47, 15
	s_cselect_b32 s44, s45, s44
	s_or_b32 s3, s2, 0x4000
	s_or_b32 s45, s44, 0x4000
	v_cmp_le_u32_e64 s[36:37], s3, v2
	v_cmp_le_u32_e32 vcc, s3, v3
	v_cmp_le_u32_e64 s[48:49], s45, v250
	v_cmp_le_u32_e64 s[50:51], s45, v251
	s_bcnt1_i32_b64 s12, s[36:37]
	s_bcnt1_i32_b64 s13, vcc
	s_bcnt1_i32_b64 s46, s[48:49]
	s_bcnt1_i32_b64 s47, s[50:51]
	s_add_i32 s13, s13, s12
	s_add_i32 s47, s47, s46
	s_cmp_gt_u32 s13, 15
	s_cselect_b32 s2, s3, s2
	s_cmp_gt_u32 s47, 15
	s_cselect_b32 s44, s45, s44
	s_or_b32 s3, s2, 0x2000
	s_or_b32 s45, s44, 0x2000
	v_cmp_le_u32_e64 s[36:37], s3, v2
	v_cmp_le_u32_e32 vcc, s3, v3
	v_cmp_le_u32_e64 s[48:49], s45, v250
	v_cmp_le_u32_e64 s[50:51], s45, v251
	s_bcnt1_i32_b64 s12, s[36:37]
	s_bcnt1_i32_b64 s13, vcc
	s_bcnt1_i32_b64 s46, s[48:49]
	s_bcnt1_i32_b64 s47, s[50:51]
	s_add_i32 s13, s13, s12
	s_add_i32 s47, s47, s46
	s_cmp_gt_u32 s13, 15
	s_cselect_b32 s2, s3, s2
	s_cmp_gt_u32 s47, 15
	s_cselect_b32 s44, s45, s44
	s_or_b32 s3, s2, 0x1000
	s_or_b32 s45, s44, 0x1000
	v_cmp_le_u32_e64 s[36:37], s3, v2
	v_cmp_le_u32_e32 vcc, s3, v3
	v_cmp_le_u32_e64 s[48:49], s45, v250
	v_cmp_le_u32_e64 s[50:51], s45, v251
	s_bcnt1_i32_b64 s12, s[36:37]
	s_bcnt1_i32_b64 s13, vcc
	s_bcnt1_i32_b64 s46, s[48:49]
	s_bcnt1_i32_b64 s47, s[50:51]
	s_add_i32 s13, s13, s12
	s_add_i32 s47, s47, s46
	s_cmp_gt_u32 s13, 15
	s_cselect_b32 s2, s3, s2
	s_cmp_gt_u32 s47, 15
	s_cselect_b32 s44, s45, s44
	s_or_b32 s3, s2, 0x800
	s_or_b32 s45, s44, 0x800
	v_cmp_le_u32_e64 s[36:37], s3, v2
	v_cmp_le_u32_e32 vcc, s3, v3
	v_cmp_le_u32_e64 s[48:49], s45, v250
	v_cmp_le_u32_e64 s[50:51], s45, v251
	s_bcnt1_i32_b64 s12, s[36:37]
	s_bcnt1_i32_b64 s13, vcc
	s_bcnt1_i32_b64 s46, s[48:49]
	s_bcnt1_i32_b64 s47, s[50:51]
	s_add_i32 s13, s13, s12
	s_add_i32 s47, s47, s46
	s_cmp_gt_u32 s13, 15
	s_cselect_b32 s2, s3, s2
	s_cmp_gt_u32 s47, 15
	s_cselect_b32 s44, s45, s44
	s_or_b32 s3, s2, 0x400
	s_or_b32 s45, s44, 0x400
	v_cmp_le_u32_e64 s[36:37], s3, v2
	v_cmp_le_u32_e32 vcc, s3, v3
	v_cmp_le_u32_e64 s[48:49], s45, v250
	v_cmp_le_u32_e64 s[50:51], s45, v251
	s_bcnt1_i32_b64 s12, s[36:37]
	s_bcnt1_i32_b64 s13, vcc
	s_bcnt1_i32_b64 s46, s[48:49]
	s_bcnt1_i32_b64 s47, s[50:51]
	s_add_i32 s13, s13, s12
	s_add_i32 s47, s47, s46
	s_cmp_gt_u32 s13, 15
	s_cselect_b32 s2, s3, s2
	s_cmp_gt_u32 s47, 15
	s_cselect_b32 s44, s45, s44
	s_or_b32 s3, s2, 0x200
	s_or_b32 s45, s44, 0x200
	v_cmp_le_u32_e64 s[36:37], s3, v2
	v_cmp_le_u32_e32 vcc, s3, v3
	v_cmp_le_u32_e64 s[48:49], s45, v250
	v_cmp_le_u32_e64 s[50:51], s45, v251
	s_bcnt1_i32_b64 s12, s[36:37]
	s_bcnt1_i32_b64 s13, vcc
	s_bcnt1_i32_b64 s46, s[48:49]
	s_bcnt1_i32_b64 s47, s[50:51]
	s_add_i32 s13, s13, s12
	s_add_i32 s47, s47, s46
	s_cmp_gt_u32 s13, 15
	s_cselect_b32 s2, s3, s2
	s_cmp_gt_u32 s47, 15
	s_cselect_b32 s44, s45, s44
	s_or_b32 s3, s2, 0x100
	s_or_b32 s45, s44, 0x100
	v_cmp_le_u32_e64 s[36:37], s3, v2
	v_cmp_le_u32_e32 vcc, s3, v3
	v_cmp_le_u32_e64 s[48:49], s45, v250
	v_cmp_le_u32_e64 s[50:51], s45, v251
	s_bcnt1_i32_b64 s12, s[36:37]
	s_bcnt1_i32_b64 s13, vcc
	s_bcnt1_i32_b64 s46, s[48:49]
	s_bcnt1_i32_b64 s47, s[50:51]
	s_add_i32 s13, s13, s12
	s_add_i32 s47, s47, s46
	s_cmp_gt_u32 s13, 15
	s_cselect_b32 s2, s3, s2
	s_cmp_gt_u32 s47, 15
	s_cselect_b32 s44, s45, s44
	s_or_b32 s3, s2, 0x80
	s_or_b32 s45, s44, 0x80
	v_cmp_le_u32_e64 s[36:37], s3, v2
	v_cmp_le_u32_e32 vcc, s3, v3
	v_cmp_le_u32_e64 s[48:49], s45, v250
	v_cmp_le_u32_e64 s[50:51], s45, v251
	s_bcnt1_i32_b64 s12, s[36:37]
	s_bcnt1_i32_b64 s13, vcc
	s_bcnt1_i32_b64 s46, s[48:49]
	s_bcnt1_i32_b64 s47, s[50:51]
	s_add_i32 s13, s13, s12
	s_add_i32 s47, s47, s46
	s_cmp_gt_u32 s13, 15
	s_cselect_b32 s2, s3, s2
	s_cmp_gt_u32 s47, 15
	s_cselect_b32 s44, s45, s44
	s_or_b32 s3, s2, 64
	s_or_b32 s45, s44, 64
	v_cmp_le_u32_e64 s[36:37], s3, v2
	v_cmp_le_u32_e32 vcc, s3, v3
	v_cmp_le_u32_e64 s[48:49], s45, v250
	v_cmp_le_u32_e64 s[50:51], s45, v251
	s_bcnt1_i32_b64 s12, s[36:37]
	s_bcnt1_i32_b64 s13, vcc
	s_bcnt1_i32_b64 s46, s[48:49]
	s_bcnt1_i32_b64 s47, s[50:51]
	s_add_i32 s13, s13, s12
	s_add_i32 s47, s47, s46
	s_cmp_gt_u32 s13, 15
	s_cselect_b32 s2, s3, s2
	s_cmp_gt_u32 s47, 15
	s_cselect_b32 s44, s45, s44
	s_or_b32 s3, s2, 32
	s_or_b32 s45, s44, 32
	v_cmp_le_u32_e64 s[36:37], s3, v2
	v_cmp_le_u32_e32 vcc, s3, v3
	v_cmp_le_u32_e64 s[48:49], s45, v250
	v_cmp_le_u32_e64 s[50:51], s45, v251
	s_bcnt1_i32_b64 s12, s[36:37]
	s_bcnt1_i32_b64 s13, vcc
	s_bcnt1_i32_b64 s46, s[48:49]
	s_bcnt1_i32_b64 s47, s[50:51]
	s_add_i32 s13, s13, s12
	s_add_i32 s47, s47, s46
	s_cmp_gt_u32 s13, 15
	s_cselect_b32 s2, s3, s2
	s_cmp_gt_u32 s47, 15
	s_cselect_b32 s44, s45, s44
	s_or_b32 s3, s2, 16
	s_or_b32 s45, s44, 16
	v_cmp_le_u32_e64 s[36:37], s3, v2
	v_cmp_le_u32_e32 vcc, s3, v3
	v_cmp_le_u32_e64 s[48:49], s45, v250
	v_cmp_le_u32_e64 s[50:51], s45, v251
	s_bcnt1_i32_b64 s12, s[36:37]
	s_bcnt1_i32_b64 s13, vcc
	s_bcnt1_i32_b64 s46, s[48:49]
	s_bcnt1_i32_b64 s47, s[50:51]
	s_add_i32 s13, s13, s12
	s_add_i32 s47, s47, s46
	s_cmp_gt_u32 s13, 15
	s_cselect_b32 s2, s3, s2
	s_cmp_gt_u32 s47, 15
	s_cselect_b32 s44, s45, s44
	s_or_b32 s3, s2, 8
	s_or_b32 s45, s44, 8
	v_cmp_le_u32_e64 s[36:37], s3, v2
	v_cmp_le_u32_e32 vcc, s3, v3
	v_cmp_le_u32_e64 s[48:49], s45, v250
	v_cmp_le_u32_e64 s[50:51], s45, v251
	s_bcnt1_i32_b64 s12, s[36:37]
	s_bcnt1_i32_b64 s13, vcc
	s_bcnt1_i32_b64 s46, s[48:49]
	s_bcnt1_i32_b64 s47, s[50:51]
	s_add_i32 s13, s13, s12
	s_add_i32 s47, s47, s46
	s_cmp_gt_u32 s13, 15
	s_cselect_b32 s2, s3, s2
	s_cmp_gt_u32 s47, 15
	s_cselect_b32 s44, s45, s44
	s_or_b32 s3, s2, 4
	s_or_b32 s45, s44, 4
	v_cmp_le_u32_e64 s[36:37], s3, v2
	v_cmp_le_u32_e32 vcc, s3, v3
	v_cmp_le_u32_e64 s[48:49], s45, v250
	v_cmp_le_u32_e64 s[50:51], s45, v251
	s_bcnt1_i32_b64 s12, s[36:37]
	s_bcnt1_i32_b64 s13, vcc
	s_bcnt1_i32_b64 s46, s[48:49]
	s_bcnt1_i32_b64 s47, s[50:51]
	s_add_i32 s13, s13, s12
	s_add_i32 s47, s47, s46
	s_cmp_gt_u32 s13, 15
	s_cselect_b32 s2, s3, s2
	s_cmp_gt_u32 s47, 15
	s_cselect_b32 s44, s45, s44
	s_or_b32 s3, s2, 2
	s_or_b32 s45, s44, 2
	v_cmp_le_u32_e64 s[36:37], s3, v2
	v_cmp_le_u32_e32 vcc, s3, v3
	v_cmp_le_u32_e64 s[48:49], s45, v250
	v_cmp_le_u32_e64 s[50:51], s45, v251
	s_bcnt1_i32_b64 s12, s[36:37]
	s_bcnt1_i32_b64 s13, vcc
	s_bcnt1_i32_b64 s46, s[48:49]
	s_bcnt1_i32_b64 s47, s[50:51]
	s_add_i32 s13, s13, s12
	s_add_i32 s47, s47, s46
	s_cmp_gt_u32 s13, 15
	s_cselect_b32 s2, s3, s2
	s_cmp_gt_u32 s47, 15
	s_cselect_b32 s44, s45, s44
	s_or_b32 s3, s2, 1
	s_or_b32 s45, s44, 1
	v_cmp_le_u32_e64 s[36:37], s3, v2
	v_cmp_le_u32_e32 vcc, s3, v3
	v_cmp_le_u32_e64 s[48:49], s45, v250
	v_cmp_le_u32_e64 s[50:51], s45, v251
	s_bcnt1_i32_b64 s12, s[36:37]
	s_bcnt1_i32_b64 s13, vcc
	s_bcnt1_i32_b64 s46, s[48:49]
	s_bcnt1_i32_b64 s47, s[50:51]
	s_add_i32 s13, s13, s12
	s_add_i32 s47, s47, s46
	s_cmp_gt_u32 s13, 15
	s_cselect_b32 s2, s3, s2
	s_cmp_gt_u32 s47, 15
	s_cselect_b32 s44, s45, s44
	v_cmp_eq_u32_e64 s[38:39], s2, v2
	v_cmp_lt_u32_e32 vcc, s2, v2
	v_cmp_lt_u32_e64 s[36:37], s2, v3
	v_cmp_eq_u32_e64 s[40:41], s2, v3
	v_and_b32_e32 v3, s38, v170
	s_bcnt1_i32_b64 s3, vcc
	s_bcnt1_i32_b64 s12, s[36:37]
	v_and_b32_e32 v2, s39, v163
	v_bcnt_u32_b32 v3, v3, 0
	v_and_b32_e32 v20, s40, v170
	s_add_i32 s3, s3, s12
	v_bcnt_u32_b32 v2, v2, v3
	v_and_b32_e32 v3, s41, v163
	v_bcnt_u32_b32 v20, v20, 0
	s_sub_i32 s12, 16, s3
	s_bcnt1_i32_b64 s2, s[38:39]
	v_bcnt_u32_b32 v3, v3, v20
	v_add_u32_e32 v3, s2, v3
	v_cmp_gt_i32_e64 s[42:43], s12, v2
	s_and_b64 s[2:3], s[38:39], s[42:43]
	v_cmp_gt_i32_e64 s[38:39], s12, v3
	s_and_b64 s[18:19], s[40:41], s[38:39]
	s_or_b64 s[2:3], vcc, s[2:3]
	v_cndmask_b32_e64 v2, 0, 1, s[2:3]
	s_or_b64 s[2:3], s[36:37], s[18:19]
	v_cmp_ne_u32_e64 s[12:13], 0, v2
	v_cndmask_b32_e64 v2, 0, 1, s[2:3]
	v_cmp_ne_u32_e32 vcc, 0, v2
	s_and_saveexec_b64 s[2:3], s[34:35]
	s_cbranch_execz .Ltk2_wa
	s_add_i32 s18, s15, 0
	s_add_i32 s18, s18, 0x22200
	v_mov_b32_e32 v20, s12
	v_mov_b32_e32 v21, s13
	v_mov_b32_e32 v22, vcc_lo
	v_mov_b32_e32 v23, vcc_hi
	v_mov_b32_e32 v2, s18
	ds_write_b128 v2, v[20:23]
.Ltk2_wa:
	s_or_b64 exec, exec, s[2:3]
	s_nop 3
	s_mov_b32 s2, s44
	v_mov_b32_e32 v2, v250
	v_mov_b32_e32 v3, v251
	s_add_i32 s15, s15, 16
	v_cmp_eq_u32_e64 s[38:39], s2, v2
	v_cmp_lt_u32_e32 vcc, s2, v2
	v_cmp_lt_u32_e64 s[36:37], s2, v3
	v_cmp_eq_u32_e64 s[40:41], s2, v3
	v_and_b32_e32 v3, s38, v170
	s_bcnt1_i32_b64 s3, vcc
	s_bcnt1_i32_b64 s12, s[36:37]
	v_and_b32_e32 v2, s39, v163
	v_bcnt_u32_b32 v3, v3, 0
	v_and_b32_e32 v20, s40, v170
	s_add_i32 s3, s3, s12
	v_bcnt_u32_b32 v2, v2, v3
	v_and_b32_e32 v3, s41, v163
	v_bcnt_u32_b32 v20, v20, 0
	s_sub_i32 s12, 16, s3
	s_bcnt1_i32_b64 s2, s[38:39]
	v_bcnt_u32_b32 v3, v3, v20
	v_add_u32_e32 v3, s2, v3
	v_cmp_gt_i32_e64 s[42:43], s12, v2
	s_and_b64 s[2:3], s[38:39], s[42:43]
	v_cmp_gt_i32_e64 s[38:39], s12, v3
	s_and_b64 s[18:19], s[40:41], s[38:39]
	s_or_b64 s[2:3], vcc, s[2:3]
	v_cndmask_b32_e64 v2, 0, 1, s[2:3]
	s_or_b64 s[2:3], s[36:37], s[18:19]
	v_cmp_ne_u32_e64 s[12:13], 0, v2
	v_cndmask_b32_e64 v2, 0, 1, s[2:3]
	v_cmp_ne_u32_e32 vcc, 0, v2
	s_and_saveexec_b64 s[2:3], s[34:35]
	s_cbranch_execz .Ltk2_wb
	s_add_i32 s18, s15, 0
	s_add_i32 s18, s18, 0x22200
	v_mov_b32_e32 v20, s12
	v_mov_b32_e32 v21, s13
	v_mov_b32_e32 v22, vcc_lo
	v_mov_b32_e32 v23, vcc_hi
	v_mov_b32_e32 v2, s18
	ds_write_b128 v2, v[20:23]
.Ltk2_wb:
	s_or_b64 exec, exec, s[2:3]
	s_add_i32 s15, s15, 16
	s_add_i32 s6, s6, 2
	v_add_u32_e32 v0, 0x408, v0
	s_cmp_eq_u32 s6, 8
	s_cbranch_scc0 .LBB0_234
